# off-diagonal QK: second accumulator's bias init issued in the gaps of the first accumulator's 4 MFMAs (MFMA order p0 x4 then p1 x4)
# baseline (speedup 1.0000x reference)
; __device__ __forceinline__ float fadd_s(float a, float b) { float r; asm("v_add_f32_e32 %0, %1, %2" : "=v"(r) : "v"(a), "v"(b)); return r; }
; __device__ __forceinline__ float fma2_s(float a, float c) { float r; asm("v_fma_f32 %0, %1, 2.0, %2" : "=v"(r) : "v"(a), "v"(c)); return r; }
; __device__ __forceinline__ void attn_unit(const Params& P, int li, LAS unsigned char* lds, int b, int h, int qb, float lam, float one_m_li) {
;     ...
;             const bool diag = (t == cw);
;             if (diag) { p0 = f32x16{}; p1 = f32x16{}; }
;             else {
;                 const float nc0 = -(sl * ((float)((cw - t) * 64) + qinf) + m), nc1 = fadd_s(nc0, sl32);
;                 float b0[4], b1[4];
;                 b0[0] = nc0; b0[1] = fadd_s(nc0, sl8); b0[2] = fma2_s(sl8, nc0); b0[3] = fadd_s(nc0, sl24);
;                 b1[0] = nc1; b1[1] = fadd_s(nc1, sl8); b1[2] = fma2_s(sl8, nc1); b1[3] = fadd_s(nc1, sl24);
; #pragma unroll
;                 for (int q = 0; q < 4; ++q) {
;                     p0[4 * q] = b0[q]; p0[4 * q + 1] = fadd_s(b0[q], sl); p0[4 * q + 2] = fma2_s(sl, b0[q]); p0[4 * q + 3] = fadd_s(b0[q], sl3);
;                     p1[4 * q] = b1[q]; p1[4 * q + 1] = fadd_s(b1[q], sl); p1[4 * q + 2] = fma2_s(sl, b1[q]); p1[4 * q + 3] = fadd_s(b1[q], sl3);
;                 }
;             }
;             __builtin_amdgcn_sched_barrier(0);
;             __builtin_amdgcn_s_setprio(1);
; #pragma unroll
;             for (int d0 = 0; d0 < 4; ++d0) {
;                 p0 = __builtin_amdgcn_mfma_f32_32x32x16_bf16(kf[2 * d0], qr[d0], p0, 0, 0, 0);
;                 p1 = __builtin_amdgcn_mfma_f32_32x32x16_bf16(kf[2 * d0 + 1], qr[d0], p1, 0, 0, 0);
;             }
.Lattn_offdiag:
	s_lshl_b32 s10, s21, 15
	s_and_b32 s22, s10, 0x18000
	v_add_u32_e32 v112, s22, v227
	v_add_u32_e32 v113, v112, v225
	ds_read_b128 v[76:79], v113
	ds_read_b128 v[68:71], v113 offset:4096
	v_add_u32_e32 v113, v112, v224
	ds_read_b128 v[72:75], v113
	ds_read_b128 v[92:95], v113 offset:4096
	v_add_u32_e32 v113, v112, v223
	v_add_u32_e32 v112, v112, v221
	ds_read_b128 v[64:67], v113
	ds_read_b128 v[84:87], v113 offset:4096
	ds_read_b128 v[88:91], v112
	ds_read_b128 v[80:83], v112 offset:4096
	s_sub_i32 s4, s31, s4
	s_lshl_b32 s4, s4, 6
	v_cvt_f32_i32_e32 v112, s4
	v_add_f32_e32 v112, v220, v112
	v_fma_f32 v112, v197, v112, v232
	v_xor_b32_e32 v96, 0x80000000, v112
	v_add_f32_e32 v112, v96, v201
	v_add_f32_e32 v100, v96, v199
	v_fma_f32 v104, v199, 2.0, v96
	v_add_f32_e32 v108, v96, v200
	v_add_f32_e32 v97, v96, v197
	v_fma_f32 v98, v197, 2.0, v96
	v_add_f32_e32 v99, v96, v198
	v_add_f32_e32 v101, v100, v197
	v_fma_f32 v102, v197, 2.0, v100
	v_add_f32_e32 v103, v100, v198
	v_add_f32_e32 v105, v104, v197
	v_fma_f32 v106, v197, 2.0, v104
	v_add_f32_e32 v107, v104, v198
	v_add_f32_e32 v109, v108, v197
	v_fma_f32 v110, v197, 2.0, v108
	v_add_f32_e32 v111, v108, v198
	s_setprio 1
	s_waitcnt lgkmcnt(0)
	v_mfma_f32_32x32x16_bf16 v[96:111], v[76:79], v[128:131], v[96:111]
	v_add_f32_e32 v116, v112, v199
	v_fma_f32 v120, v199, 2.0, v112
	v_add_f32_e32 v124, v112, v200
	v_add_f32_e32 v113, v112, v197
	v_fma_f32 v114, v197, 2.0, v112
	v_mfma_f32_32x32x16_bf16 v[96:111], v[72:75], v[132:135], v[96:111]
	v_add_f32_e32 v115, v112, v198
	v_add_f32_e32 v117, v116, v197
	v_fma_f32 v118, v197, 2.0, v116
	v_add_f32_e32 v119, v116, v198
	v_add_f32_e32 v121, v120, v197
	v_mfma_f32_32x32x16_bf16 v[96:111], v[64:67], v[136:139], v[96:111]
	v_fma_f32 v122, v197, 2.0, v120
	v_add_f32_e32 v123, v120, v198
	v_add_f32_e32 v125, v124, v197
	v_fma_f32 v126, v197, 2.0, v124
	v_add_f32_e32 v127, v124, v198
	v_mfma_f32_32x32x16_bf16 v[96:111], v[88:91], v[140:143], v[96:111]
	s_nop 0
	v_mfma_f32_32x32x16_bf16 v[112:127], v[68:71], v[128:131], v[112:127]
	v_mfma_f32_32x32x16_bf16 v[112:127], v[92:95], v[132:135], v[112:127]
	v_mfma_f32_32x32x16_bf16 v[112:127], v[84:87], v[136:139], v[112:127]
	v_mfma_f32_32x32x16_bf16 v[112:127], v[80:83], v[140:143], v[112:127]
	s_setprio 0
	s_nop 4
	v_max3_f32 v80, v96, v97, v98
	v_max3_f32 v80, v80, v99, v100
	v_max3_f32 v80, v80, v101, v102
	v_max3_f32 v80, v80, v103, v104
	v_max3_f32 v80, v80, v105, v106
	v_max3_f32 v80, v80, v107, v108
	v_max3_f32 v80, v80, v109, v110
	v_max3_f32 v80, v80, v111, v112
	v_max3_f32 v80, v80, v113, v114
	v_max3_f32 v80, v80, v115, v116
	v_max3_f32 v80, v80, v117, v118
	v_max3_f32 v80, v80, v119, v120
	v_max3_f32 v80, v80, v121, v122
	v_max3_f32 v80, v80, v123, v124
	v_max3_f32 v80, v80, v125, v126
	v_max3_f32 v80, v80, v127, v80
	s_nop 0
	v_mov_b32_e32 v81, v80
	s_nop 1
	v_permlane32_swap_b32_e32 v80, v81
	v_max_f32_e32 v233, v80, v81
	s_mov_b32 s4, 0x41000000
	v_cmp_lt_f32_e32 vcc, s4, v233
	s_mov_b64 s[22:23], 0
	s_cbranch_vccz .Lattn_od_keep
	v_max_f32_e32 v80, v233, v233
	v_max_f32_e32 v164, 0, v80
	v_exp_f32_e64 v192, -v164
	v_sub_f32_e32 v111, v111, v164
	v_sub_f32_e32 v110, v110, v164
	v_sub_f32_e32 v109, v109, v164
	v_sub_f32_e32 v108, v108, v164
	v_sub_f32_e32 v107, v107, v164
	v_sub_f32_e32 v106, v106, v164
	v_sub_f32_e32 v105, v105, v164
	v_sub_f32_e32 v104, v104, v164
	v_sub_f32_e32 v103, v103, v164
	v_sub_f32_e32 v102, v102, v164
	v_sub_f32_e32 v101, v101, v164
	v_sub_f32_e32 v100, v100, v164
	v_sub_f32_e32 v99, v99, v164
	v_sub_f32_e32 v98, v98, v164
	v_sub_f32_e32 v97, v97, v164
	v_sub_f32_e32 v96, v96, v164
	v_sub_f32_e32 v127, v127, v164
	v_sub_f32_e32 v126, v126, v164
	v_sub_f32_e32 v125, v125, v164
	v_sub_f32_e32 v124, v124, v164
	v_sub_f32_e32 v123, v123, v164
	v_sub_f32_e32 v122, v122, v164
	v_sub_f32_e32 v121, v121, v164
	v_sub_f32_e32 v120, v120, v164
	v_sub_f32_e32 v119, v119, v164
	v_sub_f32_e32 v118, v118, v164
	v_sub_f32_e32 v117, v117, v164
	v_sub_f32_e32 v116, v116, v164
	v_sub_f32_e32 v115, v115, v164
	v_sub_f32_e32 v114, v114, v164
	v_sub_f32_e32 v113, v113, v164
	v_sub_f32_e32 v112, v112, v164
	v_add_f32_e32 v187, v232, v164
	s_mov_b64 s[42:43], -1
	s_branch .LBB0_422
